# split grid barrier between merge and out phases: blocks arrive, run their first two next-group in-projection tiles (proj part-A columns only), then wait and continue with out-projection tiles and the
# speedup vs baseline: 1.0146x; 1.0077x over previous
; __device__ __forceinline__ unsigned xb_ld(unsigned* p) { return __hip_atomic_load(p, __ATOMIC_RELAXED, __HIP_MEMORY_SCOPE_AGENT); }
; __device__ __forceinline__ unsigned xb_add(unsigned* p, unsigned v) { return __hip_atomic_fetch_add(p, v, __ATOMIC_RELAXED, __HIP_MEMORY_SCOPE_AGENT); }
; #define XB_SPIN(cond, bar) do { unsigned _sp = 0; while (cond) { __builtin_amdgcn_s_sleep(1); \
;     if ((++_sp & 255u) == 0u) { if (xb_ld(&(bar)[XB_TMO])) break; if (_sp > XB_SPIN_CAP) { atomicAdd(&(bar)[XB_TMO], 1u); break; } } } } while (0)
; #define GSYNC() xcd_barrier(xb)
; __device__ __forceinline__ void xcd_barrier(const XcdBarrier& b) {
;   asm volatile("s_waitcnt vmcnt(0)" ::: "memory");
;   __syncthreads();
;   if (threadIdx.x == 0) {
;     unsigned* bar = b.bar;
;     __builtin_amdgcn_s_waitcnt(0);
;     unsigned nloc = b.st[0], nx = b.st[1];
;     if (nloc == 0u) { xcd_barrier_complete(bar, b.x, nloc, nx); b.st[0] = nloc; b.st[1] = nx; }
;     const unsigned old = xb_add(&bar[XB_XSUB(b.x)], 1u);
;     const unsigned gen = old / nloc;
;     if (old + 1u == (gen + 1u) * nloc) {
;       __builtin_amdgcn_fence(__ATOMIC_RELEASE, "agent");
;       asm volatile("s_waitcnt vmcnt(0)" ::: "memory");
;       const unsigned og = xb_add(&bar[XB_TOP], 1u);
;       const unsigned tg = og / nx;
;       if (og + 1u == (tg + 1u) * nx) xb_add(&bar[XB_TOPGEN], 1u);
;       else XB_SPIN(xb_ld(&bar[XB_TOPGEN]) == tg, bar);
;       __builtin_amdgcn_fence(__ATOMIC_ACQUIRE, "agent");
;       xb_add(&bar[XB_XGEN(b.x)], 1u);
;       asm volatile("s_waitcnt vmcnt(0)" ::: "memory");
;     } else {
;       XB_SPIN(xb_ld(&bar[XB_XGEN(b.x)]) == gen, bar);
;       __builtin_amdgcn_fence(__ATOMIC_ACQUIRE, "agent");
;       asm volatile("s_waitcnt vmcnt(0)" ::: "memory");
;     }
;   }
;   __syncthreads();
; }
; __global__ void __launch_bounds__(256, 2) k_mega(Params p) {
;     ...
;       ph_gemm_merge(p, l, smem); GSYNC();
;       ph_gemm_out(p, l, g, smem);
;       if (g + 1 < NGRP) ph_gemm_in_a(p, l, smem);
.Lgb7_poll:
	v_readlane_b32 s42, v241, 3
	v_readlane_b32 s43, v241, 4
	s_and_b64 s[42:43], s[42:43], s[38:39]
	s_cmp_lg_u64 s[42:43], 0
	s_cbranch_scc0 .Lgb7_dopoll
	v_readlane_b32 s42, v242, 3
	s_cmpk_eq_u32 s42, 0x200
	s_cbranch_scc1 .Lgb7_done

; #define GSYNC() xcd_barrier(xb)
; __device__ void ph_gemm_out(const Params& p, int l, int g, char* smem) {
;   for (int t = (int)gridDim.x - 1 - (int)blockIdx.x; t < 72 * 8; t += gridDim.x) {
; __global__ void __launch_bounds__(256, 2) k_mega(Params p) {
;     ...
;       ph_gemm_merge(p, l, smem); GSYNC();
;       ph_gemm_out(p, l, g, smem);
;       if (g + 1 < NGRP) ph_gemm_in_a(p, l, smem);
.Lgb7_done:
.LBB0_1053:
	s_or_b64 exec, exec, s[40:41]
	v_readlane_b32 s98, v240, 48
	s_add_i32 s98, s98, 1
	s_nop 0
	v_writelane_b32 v240, s98, 48
	v_readlane_b32 s12, v241, 20
	v_readlane_b32 s13, v241, 21
	s_andn2_b64 vcc, exec, s[12:13]
	s_waitcnt lgkmcnt(0)
	s_barrier
	s_mov_b32 s57, 0
	v_readlane_b32 s42, v241, 3
	v_readlane_b32 s43, v241, 4
	s_and_b64 s[42:43], s[42:43], s[38:39]
	s_cmp_lg_u64 s[42:43], 0
	s_cbranch_scc0 .Lsplit_no
	v_readlane_b32 s42, v242, 3
	s_cmpk_lg_u32 s42, 0x200
	s_cbranch_scc1 .Lsplit_no
	s_mov_b32 s57, 1
	v_readlane_b32 s46, v242, 2
	s_movk_i32 s99, 0x400
	s_branch .LBB0_1080
.Lsplit_no:
	s_cbranch_vccnz .LBB0_1076
.Lsplit_out:
	v_readlane_b32 s10, v240, 45
	s_lshl_b32 s44, s10, 2
	v_readlane_b32 s45, v241, 19
	s_branch .LBB0_1057

; __device__ void ph_gemm_in_a(const Params& p, int l, char* smem) {
;   for (int t = blockIdx.x; t < 36 * 73; t += gridDim.x) {
;     int i = t / 36, mt = t % 36;
;     int nt = i < 32 ? i : (i < 56 ? 40 + (i - 32) : (i < 72 ? 72 + (i - 56) : 128));
;     gemm_in_tile<8>(p, l, smem, mt, nt);
;   }
; __global__ void __launch_bounds__(256, 2) k_mega(Params p) {
;     ...
;       ph_gemm_out(p, l, g, smem);
;       if (g + 1 < NGRP) ph_gemm_in_a(p, l, smem);
.LBB0_1076:
	s_cmp_eq_u32 s57, 2
	s_cbranch_scc0 .Lsplit_norm
	s_mov_b32 s57, 0
	v_readlane_b32 s46, v242, 2
	s_addk_i32 s46, 0x400
	s_movk_i32 s99, 0xa44
	s_branch .LBB0_1080
.Lsplit_norm:
	v_readlane_b32 s40, v241, 3
	v_readlane_b32 s41, v241, 4
	s_and_b64 s[38:39], s[40:41], s[38:39]
	s_andn2_b64 vcc, exec, s[38:39]
	s_cbranch_vccnz .LBB0_1164
	v_readlane_b32 s46, v242, 2
	s_movk_i32 s99, 0xa44
	s_branch .LBB0_1080

; __device__ void ph_gemm_in_a(const Params& p, int l, char* smem) {
;   for (int t = blockIdx.x; t < 36 * 73; t += gridDim.x) {
.LBB0_1079:
	v_readlane_b32 s38, v242, 3
	s_add_i32 s46, s46, s38
	s_cmp_lt_i32 s46, s99
	v_readlane_b32 s39, v242, 4
	s_cbranch_scc0 .Lsplit_exit

; __device__ __forceinline__ float sigmoidf_(float x) { return __builtin_amdgcn_rcpf(1.f + __expf(-x)); }
; __device__ __forceinline__ unsigned xb_ld(unsigned* p) { return __hip_atomic_load(p, __ATOMIC_RELAXED, __HIP_MEMORY_SCOPE_AGENT); }
; __device__ __forceinline__ unsigned xb_add(unsigned* p, unsigned v) { return __hip_atomic_fetch_add(p, v, __ATOMIC_RELAXED, __HIP_MEMORY_SCOPE_AGENT); }
; template <int MF>
; __device__ __forceinline__ void gemm_in_tile(const Params& p, int l, char* smem, int mt, int nt) {
;     ...
;         if (nt >= 16 && nt < 32) {
;           float4 lb4 = *(const float4*)(p.lb + l * D + ((col - C_HGF) & 1023));
;           acc[m][n][0] = __logf(lb4.x + (1.f - lb4.x) * sigmoidf_(acc[m][n][0]));
;           acc[m][n][1] = __logf(lb4.y + (1.f - lb4.y) * sigmoidf_(acc[m][n][1]));
;           acc[m][n][2] = __logf(lb4.z + (1.f - lb4.z) * sigmoidf_(acc[m][n][2]));
;           acc[m][n][3] = __logf(lb4.w + (1.f - lb4.w) * sigmoidf_(acc[m][n][3]));
;         }
; __device__ __forceinline__ void xcd_barrier(const XcdBarrier& b) {
;   asm volatile("s_waitcnt vmcnt(0)" ::: "memory");
;   __syncthreads();
;   if (threadIdx.x == 0) {
;     unsigned* bar = b.bar;
;     __builtin_amdgcn_s_waitcnt(0);
;     unsigned nloc = b.st[0], nx = b.st[1];
;     if (nloc == 0u) { xcd_barrier_complete(bar, b.x, nloc, nx); b.st[0] = nloc; b.st[1] = nx; }
;     const unsigned old = xb_add(&bar[XB_XSUB(b.x)], 1u);
;     const unsigned gen = old / nloc;
;     if (old + 1u == (gen + 1u) * nloc) {
;       __builtin_amdgcn_fence(__ATOMIC_RELEASE, "agent");
;       asm volatile("s_waitcnt vmcnt(0)" ::: "memory");
;       const unsigned og = xb_add(&bar[XB_TOP], 1u);
;       const unsigned tg = og / nx;
;       if (og + 1u == (tg + 1u) * nx) xb_add(&bar[XB_TOPGEN], 1u);
;       else XB_SPIN(xb_ld(&bar[XB_TOPGEN]) == tg, bar);
;       __builtin_amdgcn_fence(__ATOMIC_ACQUIRE, "agent");
;       xb_add(&bar[XB_XGEN(b.x)], 1u);
;       asm volatile("s_waitcnt vmcnt(0)" ::: "memory");
;     } else {
;       XB_SPIN(xb_ld(&bar[XB_XGEN(b.x)]) == gen, bar);
;       __builtin_amdgcn_fence(__ATOMIC_ACQUIRE, "agent");
;       asm volatile("s_waitcnt vmcnt(0)" ::: "memory");
;     }
;   }
;   __syncthreads();
; }
.LBB0_1162:
	s_andn2_b64 vcc, exec, s[38:39]
	s_cbranch_vccnz .LBB0_1078
	v_mul_f32_e32 v6, 0xbfb8aa3b, v6
	v_exp_f32_e32 v6, v6
	v_mul_f32_e32 v7, 0xbfb8aa3b, v7
	v_exp_f32_e32 v7, v7
	s_mov_b32 s10, 0x3f317217
	v_add_f32_e32 v6, 1.0, v6
	v_rcp_f32_e32 v6, v6
	v_add_f32_e32 v7, 1.0, v7
	v_rcp_f32_e32 v7, v7
	v_mul_f32_e32 v8, 0xbfb8aa3b, v8
	v_exp_f32_e32 v8, v8
	v_mul_f32_e32 v9, 0xbfb8aa3b, v9
	v_exp_f32_e32 v9, v9
	v_mul_f32_e32 v2, 0xbfb8aa3b, v2
	v_add_f32_e32 v8, 1.0, v8
	v_rcp_f32_e32 v8, v8
	v_add_f32_e32 v9, 1.0, v9
	v_rcp_f32_e32 v9, v9
	v_exp_f32_e32 v2, v2
	v_mul_f32_e32 v3, 0xbfb8aa3b, v3
	v_exp_f32_e32 v3, v3
	v_mul_f32_e32 v4, 0xbfb8aa3b, v4
	v_add_f32_e32 v2, 1.0, v2
	v_rcp_f32_e32 v2, v2
	v_add_f32_e32 v3, 1.0, v3
	v_rcp_f32_e32 v3, v3
	v_exp_f32_e32 v4, v4
	v_mul_f32_e32 v5, 0xbfb8aa3b, v5
	v_exp_f32_e32 v5, v5
	v_add_f32_e32 v4, 1.0, v4
	v_rcp_f32_e32 v4, v4
	v_add_f32_e32 v5, 1.0, v5
	v_rcp_f32_e32 v5, v5
	v_mov_b32_e32 v10, v228
	v_mov_b32_e32 v11, v229
	v_mov_b32_e32 v12, v230
	v_mov_b32_e32 v13, v231
	v_sub_f32_e32 v0, 1.0, v10
	v_fma_f32 v0, v6, v0, v10
	v_cmp_gt_f32_e32 vcc, s25, v0
	s_nop 1
	v_cndmask_b32_e64 v6, 0, 32, vcc
	v_ldexp_f32 v0, v0, v6
	v_log_f32_e32 v0, v0
	s_nop 0
	v_mul_f32_e32 v6, 0x3f317217, v0
	v_fma_f32 v6, v0, s10, -v6
	v_fmac_f32_e32 v6, 0x3377d1cf, v0
	v_fmac_f32_e32 v6, 0x3f317217, v0
	v_cmp_lt_f32_e64 s[38:39], |v0|, s11
	s_nop 1
	v_cndmask_b32_e64 v0, v0, v6, s[38:39]
	v_cndmask_b32_e32 v6, 0, v171, vcc
	v_sub_f32_e32 v0, v0, v6
	v_sub_f32_e32 v6, 1.0, v11
	v_fma_f32 v6, v7, v6, v11
	v_cmp_gt_f32_e32 vcc, s25, v6
	s_nop 1
	v_cndmask_b32_e64 v7, 0, 32, vcc
	v_ldexp_f32 v6, v6, v7
	v_log_f32_e32 v6, v6
	s_nop 0
	v_mul_f32_e32 v7, 0x3f317217, v6
	v_fma_f32 v7, v6, s10, -v7
	v_fmac_f32_e32 v7, 0x3377d1cf, v6
	v_fmac_f32_e32 v7, 0x3f317217, v6
	v_cmp_lt_f32_e64 s[38:39], |v6|, s11
	s_nop 1
	v_cndmask_b32_e64 v6, v6, v7, s[38:39]
	v_cndmask_b32_e32 v7, 0, v171, vcc
	v_sub_f32_e32 v6, v6, v7
	v_sub_f32_e32 v7, 1.0, v12
	v_fma_f32 v7, v8, v7, v12
	v_cmp_gt_f32_e32 vcc, s25, v7
	v_cvt_pk_bf16_f32 v6, v0, v6
	s_nop 0
	v_cndmask_b32_e64 v8, 0, 32, vcc
	v_ldexp_f32 v7, v7, v8
	v_log_f32_e32 v7, v7
	s_nop 0
	v_mul_f32_e32 v8, 0x3f317217, v7
	v_fma_f32 v8, v7, s10, -v8
	v_fmac_f32_e32 v8, 0x3377d1cf, v7
	v_fmac_f32_e32 v8, 0x3f317217, v7
	v_cmp_lt_f32_e64 s[38:39], |v7|, s11
	s_nop 1
	v_cndmask_b32_e64 v7, v7, v8, s[38:39]
	v_cndmask_b32_e32 v8, 0, v171, vcc
	v_sub_f32_e32 v7, v7, v8
	v_sub_f32_e32 v8, 1.0, v13
	v_fmac_f32_e32 v13, v9, v8
	v_cmp_gt_f32_e32 vcc, s25, v13
	s_nop 1
	v_cndmask_b32_e64 v8, 0, 32, vcc
	v_ldexp_f32 v8, v13, v8
	v_log_f32_e32 v8, v8
	s_nop 0
	v_mul_f32_e32 v9, 0x3f317217, v8
	v_fma_f32 v9, v8, s10, -v9
	v_fmac_f32_e32 v9, 0x3377d1cf, v8
	v_fmac_f32_e32 v9, 0x3f317217, v8
	v_cmp_lt_f32_e64 s[38:39], |v8|, s11
	s_nop 1
	v_cndmask_b32_e64 v8, v8, v9, s[38:39]
	v_cndmask_b32_e32 v9, 0, v171, vcc
	v_sub_f32_e32 v8, v8, v9
	v_cvt_pk_bf16_f32 v7, v7, v8
	global_store_dwordx2 v[22:23], v[6:7], off offset:64
	v_mov_b32_e32 v6, v232
	v_mov_b32_e32 v7, v233
	v_mov_b32_e32 v8, v234
	v_mov_b32_e32 v9, v235
	v_sub_f32_e32 v0, 1.0, v6
	v_fma_f32 v0, v2, v0, v6
	v_cmp_gt_f32_e32 vcc, s25, v0
	s_nop 1
	v_cndmask_b32_e64 v2, 0, 32, vcc
	v_ldexp_f32 v0, v0, v2
	v_log_f32_e32 v0, v0
	s_nop 0
	v_mul_f32_e32 v2, 0x3f317217, v0
	v_fma_f32 v2, v0, s10, -v2
	v_fmac_f32_e32 v2, 0x3377d1cf, v0
	v_fmac_f32_e32 v2, 0x3f317217, v0
	v_cmp_lt_f32_e64 s[38:39], |v0|, s11
	s_nop 1
	v_cndmask_b32_e64 v0, v0, v2, s[38:39]
	v_cndmask_b32_e32 v2, 0, v171, vcc
	v_sub_f32_e32 v2, v0, v2
	v_sub_f32_e32 v0, 1.0, v7
	v_fma_f32 v0, v3, v0, v7
	v_cmp_gt_f32_e32 vcc, s25, v0
	s_nop 1
	v_cndmask_b32_e64 v3, 0, 32, vcc
	v_ldexp_f32 v0, v0, v3
	v_log_f32_e32 v0, v0
	s_nop 0
	v_mul_f32_e32 v3, 0x3f317217, v0
	v_fma_f32 v3, v0, s10, -v3
	v_fmac_f32_e32 v3, 0x3377d1cf, v0
	v_fmac_f32_e32 v3, 0x3f317217, v0
	v_cmp_lt_f32_e64 s[38:39], |v0|, s11
	s_nop 1
	v_cndmask_b32_e64 v0, v0, v3, s[38:39]
	v_cndmask_b32_e32 v3, 0, v171, vcc
	v_sub_f32_e32 v3, v0, v3
	v_sub_f32_e32 v0, 1.0, v8
	v_fma_f32 v0, v4, v0, v8
	v_cmp_gt_f32_e32 vcc, s25, v0
	s_nop 1
	v_cndmask_b32_e64 v4, 0, 32, vcc
	v_ldexp_f32 v0, v0, v4
	v_log_f32_e32 v0, v0
	s_nop 0
	v_mul_f32_e32 v4, 0x3f317217, v0
	v_fma_f32 v4, v0, s10, -v4
	v_fmac_f32_e32 v4, 0x3377d1cf, v0
	v_fmac_f32_e32 v4, 0x3f317217, v0
	v_cmp_lt_f32_e64 s[38:39], |v0|, s11
	s_nop 1
	v_cndmask_b32_e64 v0, v0, v4, s[38:39]
	v_cndmask_b32_e32 v4, 0, v171, vcc
	v_sub_f32_e32 v4, v0, v4
	v_sub_f32_e32 v0, 1.0, v9
	v_fmac_f32_e32 v9, v5, v0
	v_cmp_gt_f32_e32 vcc, s25, v9
	s_nop 1
	v_cndmask_b32_e64 v0, 0, 32, vcc
	v_ldexp_f32 v0, v9, v0
	v_log_f32_e32 v0, v0
	s_nop 0
	v_mul_f32_e32 v5, 0x3f317217, v0
	v_fma_f32 v5, v0, s10, -v5
	v_fmac_f32_e32 v5, 0x3377d1cf, v0
	v_fmac_f32_e32 v5, 0x3f317217, v0
	v_cmp_lt_f32_e64 s[38:39], |v0|, s11
	s_nop 1
	v_cndmask_b32_e64 v0, v0, v5, s[38:39]
	v_cndmask_b32_e32 v5, 0, v171, vcc
	v_sub_f32_e32 v5, v0, v5
	s_branch .LBB0_1078
	s_branch .LBB0_1164
.Lsplit_exit:
	s_cmp_eq_u32 s57, 1
	s_cbranch_scc1 .Lsplit_wait
	s_branch .LBB0_1164
.Lsplit_wait:
	s_mov_b32 s57, 2
	s_mov_b64 s[40:41], exec
	v_readlane_b32 s42, v242, 5
	v_readlane_b32 s43, v242, 6
	s_and_b64 s[42:43], s[40:41], s[42:43]
	s_mov_b64 exec, s[42:43]
	s_cbranch_execz .Lsplit_w_end
	ds_read_b32 v2, v166
	v_readlane_b32 s46, v240, 48
	v_readlane_b32 s44, v242, 62
	v_readlane_b32 s45, v242, 63
	s_waitcnt lgkmcnt(0)
	v_mul_lo_u32 v5, v2, s46
	s_mov_b32 s46, 0x100000
	s_nop 4

; __device__ __forceinline__ unsigned xb_ld(unsigned* p) { return __hip_atomic_load(p, __ATOMIC_RELAXED, __HIP_MEMORY_SCOPE_AGENT); }
; __device__ __forceinline__ unsigned xb_add(unsigned* p, unsigned v) { return __hip_atomic_fetch_add(p, v, __ATOMIC_RELAXED, __HIP_MEMORY_SCOPE_AGENT); }
; #define XB_SPIN(cond, bar) do { unsigned _sp = 0; while (cond) { __builtin_amdgcn_s_sleep(1); \
;     if ((++_sp & 255u) == 0u) { if (xb_ld(&(bar)[XB_TMO])) break; if (_sp > XB_SPIN_CAP) { atomicAdd(&(bar)[XB_TMO], 1u); break; } } } } while (0)
; __device__ __forceinline__ void xcd_barrier(const XcdBarrier& b) {
;   asm volatile("s_waitcnt vmcnt(0)" ::: "memory");
;   __syncthreads();
;   if (threadIdx.x == 0) {
;     unsigned* bar = b.bar;
;     __builtin_amdgcn_s_waitcnt(0);
;     unsigned nloc = b.st[0], nx = b.st[1];
;     if (nloc == 0u) { xcd_barrier_complete(bar, b.x, nloc, nx); b.st[0] = nloc; b.st[1] = nx; }
;     const unsigned old = xb_add(&bar[XB_XSUB(b.x)], 1u);
;     const unsigned gen = old / nloc;
;     if (old + 1u == (gen + 1u) * nloc) {
;       __builtin_amdgcn_fence(__ATOMIC_RELEASE, "agent");
;       asm volatile("s_waitcnt vmcnt(0)" ::: "memory");
;       const unsigned og = xb_add(&bar[XB_TOP], 1u);
;       const unsigned tg = og / nx;
;       if (og + 1u == (tg + 1u) * nx) xb_add(&bar[XB_TOPGEN], 1u);
;       else XB_SPIN(xb_ld(&bar[XB_TOPGEN]) == tg, bar);
;       __builtin_amdgcn_fence(__ATOMIC_ACQUIRE, "agent");
;       xb_add(&bar[XB_XGEN(b.x)], 1u);
;       asm volatile("s_waitcnt vmcnt(0)" ::: "memory");
;     } else {
;       XB_SPIN(xb_ld(&bar[XB_XGEN(b.x)]) == gen, bar);
;       __builtin_amdgcn_fence(__ATOMIC_ACQUIRE, "agent");
;       asm volatile("s_waitcnt vmcnt(0)" ::: "memory");
;     }
;   }
;   __syncthreads();
; }
.Lsplit_w_end:
	s_or_b64 exec, exec, s[40:41]
	s_waitcnt vmcnt(0) lgkmcnt(0)
	s_barrier
	s_branch .Lsplit_out
